# grid barrier: non-leader blocks poll the top-level generation word directly (one hop less), on top of attention tile-step rewrite
# speedup vs baseline: 1.0171x; 1.0127x over previous
.LBB0_646:
	s_or_b64 exec, exec, s[4:5]
	v_cvt_f32_u32_e32 v5, v3
	s_waitcnt vmcnt(0)
	v_readfirstlane_b32 s2, v4
	v_sub_u32_e32 v4, 0, v3
	v_rcp_iflag_f32_e32 v5, v5
	v_add_u32_e32 v6, s2, v0
	v_mul_f32_e32 v5, 0x4f7ffffe, v5
	v_cvt_u32_f32_e32 v5, v5
	v_mul_lo_u32 v0, v4, v5
	v_mul_hi_u32 v0, v5, v0
	v_add_u32_e32 v0, v5, v0
	v_mul_hi_u32 v0, v6, v0
	v_mul_lo_u32 v4, v0, v3
	v_sub_u32_e32 v4, v6, v4
	v_add_u32_e32 v5, 1, v0
	v_cmp_ge_u32_e32 vcc, v4, v3
	s_nop 1
	v_cndmask_b32_e32 v0, v0, v5, vcc
	v_sub_u32_e32 v5, v4, v3
	v_cndmask_b32_e32 v4, v4, v5, vcc
	v_add_u32_e32 v5, 1, v0
	v_cmp_ge_u32_e32 vcc, v4, v3
	v_add_u32_e32 v4, 1, v6
	s_nop 0
	v_cndmask_b32_e32 v0, v0, v5, vcc
	v_mul_lo_u32 v5, v3, v0
	v_add_u32_e32 v3, v5, v3
	v_cmp_ne_u32_e32 vcc, v4, v3
	s_and_saveexec_b64 s[2:3], vcc
	s_xor_b64 s[4:5], exec, s[2:3]
	s_cbranch_execz .LBB0_660
	v_readlane_b32 s2, v247, 19
	v_readlane_b32 s3, v247, 20
	s_waitcnt lgkmcnt(0)
	s_nop 3
	global_load_dword v2, v1, s[2:3] sc1
	s_waitcnt vmcnt(0)
	v_cmp_eq_u32_e32 vcc, v2, v0
	s_and_saveexec_b64 s[6:7], vcc
	s_cbranch_execz .LBB0_659
	s_mov_b32 s2, 1
	s_mov_b64 s[8:9], 0
	s_branch .LBB0_650
